# opening cooperative grid sync replaced by a ready-word handshake (block 0 zeroes counters write-through, drains, publishes; others poll); sharded grid barrier v2
# speedup vs baseline: 1.0271x; 1.0019x over previous
_Z14fwd_megakernel6Params:
	s_load_dwordx4 s[68:71], s[0:1], 0x80
	s_load_dwordx16 s[36:51], s[0:1], 0x0
	s_load_dwordx2 s[34:35], s[0:1], 0x90
	s_load_dwordx16 s[16:31], s[0:1], 0x40
	s_mov_b32 s12, s2
	s_waitcnt lgkmcnt(0)
	s_add_u32 s14, s70, 0x1f7a0000
	v_and_b32_e32 v1, 0x3ff, v0
	s_addc_u32 s15, s71, 0
	v_writelane_b32 v244, s16, 0
	s_sub_i32 s2, s35, s34
	s_cmp_lt_i32 s2, 2
	v_writelane_b32 v244, s17, 1
	v_writelane_b32 v244, s18, 2
	v_writelane_b32 v244, s19, 3
	v_writelane_b32 v244, s20, 4
	v_writelane_b32 v244, s21, 5
	v_writelane_b32 v244, s22, 6
	v_writelane_b32 v244, s23, 7
	v_writelane_b32 v244, s24, 8
	v_writelane_b32 v244, s25, 9
	v_writelane_b32 v244, s26, 10
	v_writelane_b32 v244, s27, 11
	v_writelane_b32 v244, s28, 12
	v_writelane_b32 v244, s29, 13
	v_writelane_b32 v244, s30, 14
	v_readfirstlane_b32 s10, v1
	v_writelane_b32 v244, s31, 15
	s_cbranch_scc1 .LBB0_14
	v_or_b32_e32 v2, s12, v1
	v_cmp_eq_u32_e32 vcc, 0, v2
	s_and_saveexec_b64 s[2:3], vcc
	s_cbranch_execz .LBB0_3
	v_mov_b32_e32 v2, 0
	global_store_dword v2, v2, s[14:15] sc1
	global_store_dword v2, v2, s[68:69] sc1
	global_store_dword v2, v2, s[68:69] offset:256 sc1
	global_store_dword v2, v2, s[68:69] offset:512 sc1
	global_store_dword v2, v2, s[68:69] offset:768 sc1
	global_store_dword v2, v2, s[68:69] offset:1024 sc1
	global_store_dword v2, v2, s[68:69] offset:1280 sc1
	global_store_dword v2, v2, s[68:69] offset:1536 sc1
	global_store_dword v2, v2, s[68:69] offset:1792 sc1
	s_waitcnt vmcnt(0)
	v_mov_b32_e32 v3, 0x13579bdf
	global_store_dword v2, v3, s[14:15] offset:64 sc1
.LBB0_3:
	s_or_b64 exec, exec, s[2:3]
	v_lshrrev_b32_e32 v2, 20, v0
	v_lshrrev_b32_e32 v0, 10, v0
	v_or_b32_e32 v0, v0, v2
	s_movk_i32 s2, 0x3ff
	v_and_or_b32 v0, v0, s2, v1
	v_cmp_eq_u32_e32 vcc, 0, v0
	s_barrier
	s_and_saveexec_b64 s[2:3], vcc
	s_cbranch_execz .LBB0_13
	v_mov_b32_e32 v0, 0
	s_mov_b32 s4, 0x13579bdf
.Lrdy_spin:
	global_load_dword v2, v0, s[14:15] offset:64 sc1
	s_waitcnt vmcnt(0)
	v_cmp_ne_u32_e32 vcc, s4, v2
	s_cbranch_vccz .Lrdy_done
	s_sleep 1
	s_branch .Lrdy_spin
.Lrdy_done:
.LBB0_13:
	s_or_b64 exec, exec, s[2:3]
	s_barrier

.LBB0_791:
	s_cmp_lg_u32 s12, 0
	s_cbranch_scc1 .Lrdy_end
	s_cmp_lg_u32 s84, 0
	s_cbranch_scc1 .Lrdy_end
	v_mbcnt_lo_u32_b32 v0, -1, 0
	v_mbcnt_hi_u32_b32 v0, -1, v0
	v_cmp_eq_u32_e32 vcc, 0, v0
	s_and_saveexec_b64 s[2:3], vcc
	v_mov_b32_e32 v0, 0
	global_store_dword v0, v0, s[14:15] offset:64 sc1
